# v71 with the readlane-SGPR to VALU wait-state padding in the gate scan raised to 2 (hazard table row 18); otherwise identical
# speedup vs baseline: 1.0074x; 1.0016x over previous
; #define LAS __attribute__((address_space(3)))
; __device__ __forceinline__ void gdn_prep_all(const Params& P, LAS unsigned char* lds, int tid, int lane, int wave, int G) {
;     ...
;         if (wq == 0) {
;             const int b = lane >> 4, c = lane & 15;
;             float d[16];
; #pragma unroll
;             for (int i = 0; i < 16; ++i) {
;                 float a0 = (i == c) ? 1.f : 0.f;
; #pragma unroll
;                 for (int k = 0; k < (i + 3) / 4; ++k) { const f32x4 l4 = *(const LAS f32x4*)(hb + LM_OFF + (16 * b + i) * 272 + (16 * b + 4 * k) * 4);
; #pragma unroll
;                     for (int e = 0; e < 4; ++e) if (4 * k + e < i) a0 -= l4[e] * d[4 * k + e]; }
;                 d[i] = a0;
;             }
; #pragma unroll
;             for (int i = 0; i < 16; ++i) *(LAS float*)(hb + DI_OFF + ((b * 16 + i) * 16 + c) * 4) = d[i];
.LBB0_462:
	s_and_b64 vcc, exec, s[14:15]
	s_cbranch_vccz .LBB0_467
	ds_read_b128 v[32:35], v172 offset:37136
	s_waitcnt lgkmcnt(0)
	ds_read_b128 v[34:37], v172 offset:37408
	s_waitcnt lgkmcnt(0)
	ds_read_b128 v[36:39], v172 offset:37680
	ds_read_b128 v[40:43], v172 offset:37952
	s_andn2_b64 vcc, exec, s[92:93]
	v_fma_f32 v31, -v121, v32, v122
	v_fma_f32 v32, -v121, v34, v123
	v_fma_f32 v50, -v35, v31, v32
	s_waitcnt lgkmcnt(1)
	v_fma_f32 v32, -v121, v36, v124
	v_fma_f32 v32, -v37, v31, v32
	v_fma_f32 v51, -v38, v50, v32
	ds_read_b128 v[32:35], v172 offset:38224
	s_waitcnt lgkmcnt(1)
	v_fma_f32 v36, -v121, v40, v125
	v_fma_f32 v36, -v31, v41, v36
	v_fma_f32 v36, -v42, v50, v36
	v_fma_f32 v52, -v43, v51, v36
	ds_read_b128 v[36:39], v172 offset:38240
	s_waitcnt lgkmcnt(1)
	v_fma_f32 v32, -v121, v32, v126
	s_waitcnt lgkmcnt(0)
	ds_read_b128 v[38:41], v172 offset:38496
	v_fma_f32 v32, -v31, v33, v32
	v_fma_f32 v32, -v34, v50, v32
	v_fma_f32 v32, -v35, v51, v32
	v_fma_f32 v53, -v36, v52, v32
	ds_read_b128 v[32:35], v172 offset:38512
	s_waitcnt lgkmcnt(0)
	v_fma_f32 v34, -v121, v38, v127
	v_fma_f32 v34, -v31, v39, v34
	v_fma_f32 v38, -v50, v40, v34
	ds_read_b128 v[34:37], v172 offset:38768
	v_fma_f32 v38, -v41, v51, v38
	v_fma_f32 v32, -v32, v52, v38
	v_fma_f32 v54, -v33, v53, v32
	ds_read_b128 v[38:41], v172 offset:38784
	s_waitcnt lgkmcnt(1)
	v_fma_f32 v32, -v121, v34, v128
	v_fma_f32 v32, -v31, v35, v32
	v_fma_f32 v32, -v50, v36, v32
	v_fma_f32 v36, -v51, v37, v32
	ds_read_b128 v[32:35], v172 offset:39040
	s_waitcnt lgkmcnt(1)
	v_fma_f32 v36, -v52, v38, v36
	v_fma_f32 v36, -v39, v53, v36
	v_fma_f32 v55, -v40, v54, v36
	ds_read_b128 v[36:39], v172 offset:39056
	s_waitcnt lgkmcnt(1)
	v_fma_f32 v32, -v121, v32, v129
	v_fma_f32 v32, -v31, v33, v32
	v_fma_f32 v32, -v50, v34, v32
	v_fma_f32 v32, -v51, v35, v32
	s_waitcnt lgkmcnt(0)
	v_fma_f32 v36, -v52, v36, v32
	ds_read_b128 v[32:35], v172 offset:39312
	v_fma_f32 v36, -v53, v37, v36
	v_fma_f32 v36, -v38, v54, v36
	v_fma_f32 v56, -v39, v55, v36
	ds_read_b128 v[36:39], v172 offset:39328
	s_waitcnt lgkmcnt(1)
	v_fma_f32 v32, -v121, v32, v130
	v_fma_f32 v32, -v31, v33, v32
	v_fma_f32 v32, -v50, v34, v32
	v_fma_f32 v32, -v51, v35, v32
	s_waitcnt lgkmcnt(0)
	v_fma_f32 v36, -v52, v36, v32
	ds_read_b128 v[32:35], v172 offset:39344
	ds_read_b128 v[40:43], v172 offset:39584
	s_waitcnt lgkmcnt(1)
	v_fma_f32 v33, -v53, v37, v36
	v_fma_f32 v33, -v38, v54, v33
	v_fma_f32 v33, -v39, v55, v33
	v_fma_f32 v57, -v32, v56, v33
	ds_read_b128 v[32:35], v172 offset:39600
	s_waitcnt lgkmcnt(1)
	v_fma_f32 v36, -v121, v40, v131
	v_fma_f32 v36, -v31, v41, v36
	v_fma_f32 v36, -v50, v42, v36
	v_fma_f32 v40, -v51, v43, v36
	ds_read_b128 v[36:39], v172 offset:39616
	s_waitcnt lgkmcnt(1)
	v_fma_f32 v32, -v52, v32, v40
	v_fma_f32 v32, -v53, v33, v32
	s_waitcnt lgkmcnt(0)
	ds_read_b128 v[38:41], v172 offset:39856
	v_fma_f32 v32, -v54, v34, v32
	v_fma_f32 v32, -v35, v55, v32
	v_fma_f32 v32, -v36, v56, v32
	v_fma_f32 v58, -v37, v57, v32
	ds_read_b128 v[32:35], v172 offset:39872
	s_waitcnt lgkmcnt(1)
	v_fma_f32 v36, -v121, v38, v132
	v_fma_f32 v36, -v31, v39, v36
	v_fma_f32 v36, -v50, v40, v36
	v_fma_f32 v36, -v51, v41, v36
	s_waitcnt lgkmcnt(0)
	v_fma_f32 v32, -v52, v32, v36
	ds_read_b128 v[36:39], v172 offset:39888
	ds_read_b128 v[40:43], v172 offset:40128
	v_fma_f32 v32, -v53, v33, v32
	v_fma_f32 v32, -v54, v34, v32
	v_fma_f32 v32, -v55, v35, v32
	s_waitcnt lgkmcnt(1)
	v_fma_f32 v32, -v56, v36, v32
	v_fma_f32 v32, -v37, v57, v32
	v_fma_f32 v59, -v38, v58, v32
	ds_read_b128 v[32:35], v172 offset:40144
	s_waitcnt lgkmcnt(1)
	v_fma_f32 v36, -v121, v40, v133
	v_fma_f32 v36, -v31, v41, v36
	v_fma_f32 v36, -v50, v42, v36
	v_fma_f32 v40, -v51, v43, v36
	ds_read_b128 v[36:39], v172 offset:40160
	s_waitcnt lgkmcnt(1)
	v_fma_f32 v32, -v52, v32, v40
	v_fma_f32 v32, -v53, v33, v32
	v_fma_f32 v32, -v54, v34, v32
	v_fma_f32 v32, -v55, v35, v32
	s_waitcnt lgkmcnt(0)
	v_fma_f32 v36, -v56, v36, v32
	ds_read_b128 v[32:35], v172 offset:40400
	v_fma_f32 v36, -v57, v37, v36
	v_fma_f32 v36, -v38, v58, v36
	v_fma_f32 v60, -v39, v59, v36
	ds_read_b128 v[36:39], v172 offset:40416
	s_waitcnt lgkmcnt(1)
	v_fma_f32 v32, -v121, v32, v134
	v_fma_f32 v32, -v31, v33, v32
	v_fma_f32 v32, -v50, v34, v32
	v_fma_f32 v32, -v51, v35, v32
	s_waitcnt lgkmcnt(0)
	v_fma_f32 v36, -v52, v36, v32
	ds_read_b128 v[32:35], v172 offset:40432
	v_fma_f32 v36, -v53, v37, v36
	v_fma_f32 v36, -v54, v38, v36
	v_fma_f32 v40, -v55, v39, v36
	ds_read_b128 v[36:39], v172 offset:40448
	s_waitcnt lgkmcnt(1)
	v_fma_f32 v32, -v56, v32, v40
	s_waitcnt lgkmcnt(0)
	ds_read_b128 v[38:41], v172 offset:40672
	v_fma_f32 v32, -v57, v33, v32
	v_fma_f32 v32, -v34, v58, v32
	v_fma_f32 v32, -v35, v59, v32
	v_fma_f32 v61, -v36, v60, v32
	ds_read_b128 v[32:35], v172 offset:40688
	s_waitcnt lgkmcnt(1)
	v_fma_f32 v36, -v121, v38, v135
	v_fma_f32 v36, -v31, v39, v36
	v_fma_f32 v36, -v50, v40, v36
	v_fma_f32 v36, -v51, v41, v36
	s_waitcnt lgkmcnt(0)
	v_fma_f32 v32, -v52, v32, v36
	ds_read_b128 v[36:39], v172 offset:40704
	v_fma_f32 v32, -v53, v33, v32
	v_fma_f32 v32, -v54, v34, v32
	v_fma_f32 v40, -v55, v35, v32
	ds_read_b128 v[32:35], v172 offset:40720
	s_waitcnt lgkmcnt(0)
	v_fma_f32 v34, -v56, v36, v40
	v_fma_f32 v34, -v57, v37, v34
	v_fma_f32 v34, -v58, v38, v34
	v_fma_f32 v34, -v39, v59, v34
	v_fma_f32 v32, -v32, v60, v34
	ds_read_b128 v[34:37], v173 offset:36864
	v_fma_f32 v32, -v33, v61, v32
	ds_read_b128 v[38:41], v173 offset:36880
	ds_read_b128 v[42:45], v173 offset:36896
	ds_read_b128 v[46:49], v173 offset:36912
	s_waitcnt lgkmcnt(3)
	v_fma_f32 v33, -v121, v34, v136
	v_fma_f32 v33, -v31, v35, v33
	v_fma_f32 v33, -v50, v36, v33
	v_fma_f32 v33, -v51, v37, v33
	s_waitcnt lgkmcnt(2)
	v_fma_f32 v33, -v52, v38, v33
	v_fma_f32 v33, -v53, v39, v33
	v_fma_f32 v33, -v54, v40, v33
	v_fma_f32 v33, -v55, v41, v33
	s_waitcnt lgkmcnt(1)
	v_fma_f32 v33, -v56, v42, v33
	v_fma_f32 v33, -v57, v43, v33
	v_fma_f32 v33, -v58, v44, v33
	v_fma_f32 v33, -v59, v45, v33
	s_waitcnt lgkmcnt(0)
	v_fma_f32 v33, -v60, v46, v33
	v_fma_f32 v33, -v47, v61, v33
	v_add_u32_e32 v34, 0xd800, v174
	v_fma_f32 v33, -v48, v32, v33
	ds_write2_b32 v34, v121, v31 offset0:64 offset1:80
	ds_write2_b32 v34, v50, v51 offset0:96 offset1:112
	ds_write2_b32 v34, v52, v53 offset0:128 offset1:144
	ds_write2_b32 v34, v54, v55 offset0:160 offset1:176
	ds_write2_b32 v34, v56, v57 offset0:192 offset1:208
	ds_write2_b32 v34, v58, v59 offset0:224 offset1:240
	v_add_u32_e32 v31, 0xdc00, v174
	ds_write2_b32 v31, v60, v61 offset1:16
	ds_write_b32 v174, v32 offset:56448
	ds_write_b32 v175, v33 offset:55552
	s_cbranch_vccnz .LBB0_467
	s_waitcnt vmcnt(1)
	v_mov_b32_e32 v32, v107
	v_readlane_b32 s18, v247, 54
	v_readlane_b32 s19, v247, 55
	v_add_f32_dpp v32, v32, v32 row_shr:1 row_mask:0xf bank_mask:0xf
	s_nop 1
	v_add_f32_dpp v32, v32, v32 row_shr:2 row_mask:0xf bank_mask:0xf
	s_nop 1
	v_add_f32_dpp v32, v32, v32 row_shr:4 row_mask:0xf bank_mask:0xf
	s_nop 1
	v_add_f32_dpp v32, v32, v32 row_shr:8 row_mask:0xf bank_mask:0xf
	s_nop 1
	v_add_f32_dpp v32, v32, v32 row_bcast:15 row_mask:0xa bank_mask:0xf
	s_nop 1
	v_add_f32_dpp v32, v32, v32 row_bcast:31 row_mask:0xc bank_mask:0xf
	s_nop 1
	v_readlane_b32 s12, v32, 63
	s_nop 1
	v_mov_b32_e32 v31, s12
	v_mul_f32_e32 v33, 0x3fb8aa3b, v32
	v_exp_f32_e32 v33, v33
	s_and_b64 s[12:13], s[60:61], exec
	s_cselect_b32 s11, s4, s83
	s_waitcnt lgkmcnt(0)
	v_sub_f32_e32 v34, v31, v32
	v_mul_f32_e32 v34, 0x3fb8aa3b, v34
	v_exp_f32_e32 v34, v34
	v_lshl_add_u32 v35, v1, 2, s11
	s_waitcnt vmcnt(0)
	ds_write2st64_b32 v35, v32, v108 offset1:1
	v_mul_f32_e32 v32, v108, v33
	ds_write2st64_b32 v35, v33, v34 offset0:2 offset1:3
	ds_write_b32 v35, v32 offset:1024
	s_and_saveexec_b64 s[14:15], s[18:19]
	s_cbranch_execz .LBB0_466
	s_lshl_b32 s11, s2, 1
	s_and_b32 s12, s11, 6
	s_add_i32 s12, s12, s82
	s_and_b32 s11, s11, -8
	s_add_i32 s12, s12, s11
	v_mul_f32_e32 v31, 0x3fb8aa3b, v31
	s_ashr_i32 s13, s12, 31
	v_exp_f32_e32 v31, v31
	s_lshl_b64 s[12:13], s[12:13], 2
	s_add_u32 s12, s37, s12
	v_readlane_b32 s11, v247, 53
	s_addc_u32 s13, s11, s13
	global_store_dword v30, v31, s[12:13]
